# v22 + grid barriers: non-leader blocks poll the global generation word directly (one poll hop less per barrier)
# baseline (speedup 1.0000x reference)
; __device__ __forceinline__ unsigned xb_ld(unsigned* p)              { return __hip_atomic_load(p, __ATOMIC_RELAXED, __HIP_MEMORY_SCOPE_AGENT); }
; __device__ __forceinline__ unsigned xb_add(unsigned* p, unsigned v) { return __hip_atomic_fetch_add(p, v, __ATOMIC_RELAXED, __HIP_MEMORY_SCOPE_AGENT); }
; #define XB_SPIN(cond, bar) do { unsigned _sp = 0; while (cond) { __builtin_amdgcn_s_sleep(1); \
;     if ((++_sp & 255u) == 0u) { if (xb_ld(&(bar)[XB_TMO])) break; if (_sp > XB_SPIN_CAP) { atomicAdd(&(bar)[XB_TMO], 1u); break; } } } } while (0)
; __device__ __forceinline__ void xcd_barrier(const XcdBarrier& b) {
;     ...
;         const unsigned old = xb_add(&bar[XB_XSUB(b.x)], 1u);
;         const unsigned gen = old / nloc;
;         if (old + 1u == (gen + 1u) * nloc) {
;             __builtin_amdgcn_fence(__ATOMIC_RELEASE, "agent");
;             asm volatile("s_waitcnt vmcnt(0)" ::: "memory");
;             const unsigned og = xb_add(&bar[XB_TOP], 1u);
;             const unsigned tg = og / nx;
;             if (og + 1u == (tg + 1u) * nx) xb_add(&bar[XB_TOPGEN], 1u);
;             else XB_SPIN(xb_ld(&bar[XB_TOPGEN]) == tg, bar);
;             __builtin_amdgcn_fence(__ATOMIC_ACQUIRE, "agent");
;             xb_add(&bar[XB_XGEN(b.x)], 1u);
;             asm volatile("s_waitcnt vmcnt(0)" ::: "memory");
;         } else {
;             XB_SPIN(xb_ld(&bar[XB_XGEN(b.x)]) == gen, bar);
;             __builtin_amdgcn_fence(__ATOMIC_ACQUIRE, "agent");
;             asm volatile("s_waitcnt vmcnt(0)" ::: "memory");
;         }
.LBB0_140:
	s_or_b64 exec, exec, s[8:9]
	v_cvt_f32_u32_e32 v4, v2
	s_waitcnt vmcnt(0)
	v_readfirstlane_b32 s6, v3
	v_sub_u32_e32 v3, 0, v2
	v_rcp_iflag_f32_e32 v4, v4
	v_add_u32_e32 v5, s6, v1
	v_mul_f32_e32 v4, 0x4f7ffffe, v4
	v_cvt_u32_f32_e32 v4, v4
	v_mul_lo_u32 v1, v3, v4
	v_mul_hi_u32 v1, v4, v1
	v_add_u32_e32 v1, v4, v1
	v_mul_hi_u32 v1, v5, v1
	v_mul_lo_u32 v3, v1, v2
	v_sub_u32_e32 v3, v5, v3
	v_add_u32_e32 v4, 1, v1
	v_cmp_ge_u32_e32 vcc, v3, v2
	s_nop 1
	v_cndmask_b32_e32 v1, v1, v4, vcc
	v_sub_u32_e32 v4, v3, v2
	v_cndmask_b32_e32 v3, v3, v4, vcc
	v_add_u32_e32 v4, 1, v1
	v_cmp_ge_u32_e32 vcc, v3, v2
	v_add_u32_e32 v3, 1, v5
	s_nop 0
	v_cndmask_b32_e32 v1, v1, v4, vcc
	v_mul_lo_u32 v4, v2, v1
	v_add_u32_e32 v2, v4, v2
	v_cmp_ne_u32_e32 vcc, v3, v2
	s_and_saveexec_b64 s[6:7], vcc
	s_xor_b64 s[6:7], exec, s[6:7]
	s_cbranch_execz .LBB0_154
	s_waitcnt lgkmcnt(0)
	v_mov_b32_e32 v0, 0x3500
	global_load_dword v0, v0, s[34:35] sc1
	s_add_u32 s38, s34, 0x3500
	s_addc_u32 s39, s35, 0
	s_waitcnt vmcnt(0)
	v_cmp_eq_u32_e32 vcc, v0, v1
	s_and_saveexec_b64 s[8:9], vcc
	s_cbranch_execz .LBB0_153
	s_add_u32 s18, s30, 0x20200
	s_addc_u32 s19, s31, 0
	s_mov_b32 s58, 1
	s_mov_b64 s[42:43], 0
	v_mov_b32_e32 v0, 0
	s_branch .LBB0_144

; __device__ __forceinline__ unsigned xb_ld(unsigned* p)              { return __hip_atomic_load(p, __ATOMIC_RELAXED, __HIP_MEMORY_SCOPE_AGENT); }
; __device__ __forceinline__ unsigned xb_add(unsigned* p, unsigned v) { return __hip_atomic_fetch_add(p, v, __ATOMIC_RELAXED, __HIP_MEMORY_SCOPE_AGENT); }
; #define XB_SPIN(cond, bar) do { unsigned _sp = 0; while (cond) { __builtin_amdgcn_s_sleep(1); \
;     if ((++_sp & 255u) == 0u) { if (xb_ld(&(bar)[XB_TMO])) break; if (_sp > XB_SPIN_CAP) { atomicAdd(&(bar)[XB_TMO], 1u); break; } } } } while (0)
; __device__ __forceinline__ void xcd_barrier(const XcdBarrier& b) {
;     ...
;         const unsigned old = xb_add(&bar[XB_XSUB(b.x)], 1u);
;         const unsigned gen = old / nloc;
;         if (old + 1u == (gen + 1u) * nloc) {
;             __builtin_amdgcn_fence(__ATOMIC_RELEASE, "agent");
;             asm volatile("s_waitcnt vmcnt(0)" ::: "memory");
;             const unsigned og = xb_add(&bar[XB_TOP], 1u);
;             const unsigned tg = og / nx;
;             if (og + 1u == (tg + 1u) * nx) xb_add(&bar[XB_TOPGEN], 1u);
;             else XB_SPIN(xb_ld(&bar[XB_TOPGEN]) == tg, bar);
;             __builtin_amdgcn_fence(__ATOMIC_ACQUIRE, "agent");
;             xb_add(&bar[XB_XGEN(b.x)], 1u);
;             asm volatile("s_waitcnt vmcnt(0)" ::: "memory");
;         } else {
;             XB_SPIN(xb_ld(&bar[XB_XGEN(b.x)]) == gen, bar);
;             __builtin_amdgcn_fence(__ATOMIC_ACQUIRE, "agent");
;             asm volatile("s_waitcnt vmcnt(0)" ::: "memory");
;         }
.LBB0_226:
	s_or_b64 exec, exec, s[8:9]
	v_cvt_f32_u32_e32 v4, v2
	s_waitcnt vmcnt(0)
	v_readfirstlane_b32 s6, v3
	v_sub_u32_e32 v3, 0, v2
	v_rcp_iflag_f32_e32 v4, v4
	v_add_u32_e32 v5, s6, v1
	v_mul_f32_e32 v4, 0x4f7ffffe, v4
	v_cvt_u32_f32_e32 v4, v4
	v_mul_lo_u32 v1, v3, v4
	v_mul_hi_u32 v1, v4, v1
	v_add_u32_e32 v1, v4, v1
	v_mul_hi_u32 v1, v5, v1
	v_mul_lo_u32 v3, v1, v2
	v_sub_u32_e32 v3, v5, v3
	v_add_u32_e32 v4, 1, v1
	v_cmp_ge_u32_e32 vcc, v3, v2
	s_nop 1
	v_cndmask_b32_e32 v1, v1, v4, vcc
	v_sub_u32_e32 v4, v3, v2
	v_cndmask_b32_e32 v3, v3, v4, vcc
	v_add_u32_e32 v4, 1, v1
	v_cmp_ge_u32_e32 vcc, v3, v2
	v_add_u32_e32 v3, 1, v5
	s_nop 0
	v_cndmask_b32_e32 v1, v1, v4, vcc
	v_mul_lo_u32 v4, v2, v1
	v_add_u32_e32 v2, v4, v2
	v_cmp_ne_u32_e32 vcc, v3, v2
	s_and_saveexec_b64 s[6:7], vcc
	s_xor_b64 s[6:7], exec, s[6:7]
	s_cbranch_execz .LBB0_240
	s_waitcnt lgkmcnt(0)
	v_mov_b32_e32 v0, 0x3500
	global_load_dword v0, v0, s[34:35] sc1
	s_add_u32 s24, s34, 0x3500
	s_addc_u32 s25, s35, 0
	s_waitcnt vmcnt(0)
	v_cmp_eq_u32_e32 vcc, v0, v1
	s_and_saveexec_b64 s[8:9], vcc
	s_cbranch_execz .LBB0_239
	s_add_u32 s22, s30, 0x20200
	s_addc_u32 s23, s31, 0
	s_mov_b32 s54, 1
	s_mov_b64 s[38:39], 0
	v_mov_b32_e32 v0, 0
	s_branch .LBB0_230

; __device__ __forceinline__ unsigned xb_ld(unsigned* p)              { return __hip_atomic_load(p, __ATOMIC_RELAXED, __HIP_MEMORY_SCOPE_AGENT); }
; __device__ __forceinline__ unsigned xb_add(unsigned* p, unsigned v) { return __hip_atomic_fetch_add(p, v, __ATOMIC_RELAXED, __HIP_MEMORY_SCOPE_AGENT); }
; #define XB_SPIN(cond, bar) do { unsigned _sp = 0; while (cond) { __builtin_amdgcn_s_sleep(1); \
;     if ((++_sp & 255u) == 0u) { if (xb_ld(&(bar)[XB_TMO])) break; if (_sp > XB_SPIN_CAP) { atomicAdd(&(bar)[XB_TMO], 1u); break; } } } } while (0)
; __device__ __forceinline__ void xcd_barrier(const XcdBarrier& b) {
;     ...
;         const unsigned old = xb_add(&bar[XB_XSUB(b.x)], 1u);
;         const unsigned gen = old / nloc;
;         if (old + 1u == (gen + 1u) * nloc) {
;             __builtin_amdgcn_fence(__ATOMIC_RELEASE, "agent");
;             asm volatile("s_waitcnt vmcnt(0)" ::: "memory");
;             const unsigned og = xb_add(&bar[XB_TOP], 1u);
;             const unsigned tg = og / nx;
;             if (og + 1u == (tg + 1u) * nx) xb_add(&bar[XB_TOPGEN], 1u);
;             else XB_SPIN(xb_ld(&bar[XB_TOPGEN]) == tg, bar);
;             __builtin_amdgcn_fence(__ATOMIC_ACQUIRE, "agent");
;             xb_add(&bar[XB_XGEN(b.x)], 1u);
;             asm volatile("s_waitcnt vmcnt(0)" ::: "memory");
;         } else {
;             XB_SPIN(xb_ld(&bar[XB_XGEN(b.x)]) == gen, bar);
;             __builtin_amdgcn_fence(__ATOMIC_ACQUIRE, "agent");
;             asm volatile("s_waitcnt vmcnt(0)" ::: "memory");
;         }
.LBB0_397:
	s_or_b64 exec, exec, s[22:23]
	v_cvt_f32_u32_e32 v4, v2
	s_waitcnt vmcnt(0)
	v_readfirstlane_b32 s8, v3
	v_sub_u32_e32 v3, 0, v2
	v_rcp_iflag_f32_e32 v4, v4
	v_add_u32_e32 v5, s8, v1
	v_mul_f32_e32 v4, 0x4f7ffffe, v4
	v_cvt_u32_f32_e32 v4, v4
	v_mul_lo_u32 v1, v3, v4
	v_mul_hi_u32 v1, v4, v1
	v_add_u32_e32 v1, v4, v1
	v_mul_hi_u32 v1, v5, v1
	v_mul_lo_u32 v3, v1, v2
	v_sub_u32_e32 v3, v5, v3
	v_add_u32_e32 v4, 1, v1
	v_cmp_ge_u32_e32 vcc, v3, v2
	s_nop 1
	v_cndmask_b32_e32 v1, v1, v4, vcc
	v_sub_u32_e32 v4, v3, v2
	v_cndmask_b32_e32 v3, v3, v4, vcc
	v_add_u32_e32 v4, 1, v1
	v_cmp_ge_u32_e32 vcc, v3, v2
	v_add_u32_e32 v3, 1, v5
	s_nop 0
	v_cndmask_b32_e32 v1, v1, v4, vcc
	v_mul_lo_u32 v4, v2, v1
	v_add_u32_e32 v2, v4, v2
	v_cmp_ne_u32_e32 vcc, v3, v2
	s_and_saveexec_b64 s[8:9], vcc
	s_xor_b64 s[8:9], exec, s[8:9]
	s_cbranch_execz .LBB0_411
	s_waitcnt lgkmcnt(0)
	v_mov_b32_e32 v0, 0x3500
	global_load_dword v0, v0, s[34:35] sc1
	s_add_u32 s38, s34, 0x3500
	s_addc_u32 s39, s35, 0
	s_waitcnt vmcnt(0)
	v_cmp_eq_u32_e32 vcc, v0, v1
	s_and_saveexec_b64 s[22:23], vcc
	s_cbranch_execz .LBB0_410
	s_add_u32 s24, s30, 0x20200
	s_addc_u32 s25, s31, 0
	s_mov_b32 s54, 1
	s_mov_b64 s[42:43], 0
	v_mov_b32_e32 v0, 0
	s_branch .LBB0_401

; __device__ __forceinline__ unsigned xb_ld(unsigned* p)              { return __hip_atomic_load(p, __ATOMIC_RELAXED, __HIP_MEMORY_SCOPE_AGENT); }
; __device__ __forceinline__ unsigned xb_add(unsigned* p, unsigned v) { return __hip_atomic_fetch_add(p, v, __ATOMIC_RELAXED, __HIP_MEMORY_SCOPE_AGENT); }
; #define XB_SPIN(cond, bar) do { unsigned _sp = 0; while (cond) { __builtin_amdgcn_s_sleep(1); \
;     if ((++_sp & 255u) == 0u) { if (xb_ld(&(bar)[XB_TMO])) break; if (_sp > XB_SPIN_CAP) { atomicAdd(&(bar)[XB_TMO], 1u); break; } } } } while (0)
; __device__ __forceinline__ void xcd_barrier(const XcdBarrier& b) {
;     ...
;         const unsigned old = xb_add(&bar[XB_XSUB(b.x)], 1u);
;         const unsigned gen = old / nloc;
;         if (old + 1u == (gen + 1u) * nloc) {
;             __builtin_amdgcn_fence(__ATOMIC_RELEASE, "agent");
;             asm volatile("s_waitcnt vmcnt(0)" ::: "memory");
;             const unsigned og = xb_add(&bar[XB_TOP], 1u);
;             const unsigned tg = og / nx;
;             if (og + 1u == (tg + 1u) * nx) xb_add(&bar[XB_TOPGEN], 1u);
;             else XB_SPIN(xb_ld(&bar[XB_TOPGEN]) == tg, bar);
;             __builtin_amdgcn_fence(__ATOMIC_ACQUIRE, "agent");
;             xb_add(&bar[XB_XGEN(b.x)], 1u);
;             asm volatile("s_waitcnt vmcnt(0)" ::: "memory");
;         } else {
;             XB_SPIN(xb_ld(&bar[XB_XGEN(b.x)]) == gen, bar);
;             __builtin_amdgcn_fence(__ATOMIC_ACQUIRE, "agent");
;             asm volatile("s_waitcnt vmcnt(0)" ::: "memory");
;         }
.LBB0_528:
	s_or_b64 exec, exec, s[22:23]
	v_cvt_f32_u32_e32 v4, v2
	s_waitcnt vmcnt(0)
	v_readfirstlane_b32 s8, v3
	v_sub_u32_e32 v3, 0, v2
	v_rcp_iflag_f32_e32 v4, v4
	v_add_u32_e32 v5, s8, v1
	v_mul_f32_e32 v4, 0x4f7ffffe, v4
	v_cvt_u32_f32_e32 v4, v4
	v_mul_lo_u32 v1, v3, v4
	v_mul_hi_u32 v1, v4, v1
	v_add_u32_e32 v1, v4, v1
	v_mul_hi_u32 v1, v5, v1
	v_mul_lo_u32 v3, v1, v2
	v_sub_u32_e32 v3, v5, v3
	v_add_u32_e32 v4, 1, v1
	v_cmp_ge_u32_e32 vcc, v3, v2
	s_nop 1
	v_cndmask_b32_e32 v1, v1, v4, vcc
	v_sub_u32_e32 v4, v3, v2
	v_cndmask_b32_e32 v3, v3, v4, vcc
	v_add_u32_e32 v4, 1, v1
	v_cmp_ge_u32_e32 vcc, v3, v2
	v_add_u32_e32 v3, 1, v5
	s_nop 0
	v_cndmask_b32_e32 v1, v1, v4, vcc
	v_mul_lo_u32 v4, v2, v1
	v_add_u32_e32 v2, v4, v2
	v_cmp_ne_u32_e32 vcc, v3, v2
	s_and_saveexec_b64 s[8:9], vcc
	s_xor_b64 s[8:9], exec, s[8:9]
	s_cbranch_execz .LBB0_542
	s_waitcnt lgkmcnt(0)
	v_mov_b32_e32 v0, 0x3500
	global_load_dword v0, v0, s[34:35] sc1
	s_add_u32 s36, s34, 0x3500
	s_addc_u32 s37, s35, 0
	s_waitcnt vmcnt(0)
	v_cmp_eq_u32_e32 vcc, v0, v1
	s_and_saveexec_b64 s[22:23], vcc
	s_cbranch_execz .LBB0_541
	s_add_u32 s24, s30, 0x20200
	s_addc_u32 s25, s31, 0
	s_mov_b32 s48, 1
	s_mov_b64 s[38:39], 0
	v_mov_b32_e32 v0, 0
	s_branch .LBB0_532

; __device__ __forceinline__ unsigned xb_ld(unsigned* p)              { return __hip_atomic_load(p, __ATOMIC_RELAXED, __HIP_MEMORY_SCOPE_AGENT); }
; __device__ __forceinline__ unsigned xb_add(unsigned* p, unsigned v) { return __hip_atomic_fetch_add(p, v, __ATOMIC_RELAXED, __HIP_MEMORY_SCOPE_AGENT); }
; #define XB_SPIN(cond, bar) do { unsigned _sp = 0; while (cond) { __builtin_amdgcn_s_sleep(1); \
;     if ((++_sp & 255u) == 0u) { if (xb_ld(&(bar)[XB_TMO])) break; if (_sp > XB_SPIN_CAP) { atomicAdd(&(bar)[XB_TMO], 1u); break; } } } } while (0)
; __device__ __forceinline__ void xcd_barrier(const XcdBarrier& b) {
;     ...
;         const unsigned old = xb_add(&bar[XB_XSUB(b.x)], 1u);
;         const unsigned gen = old / nloc;
;         if (old + 1u == (gen + 1u) * nloc) {
;             __builtin_amdgcn_fence(__ATOMIC_RELEASE, "agent");
;             asm volatile("s_waitcnt vmcnt(0)" ::: "memory");
;             const unsigned og = xb_add(&bar[XB_TOP], 1u);
;             const unsigned tg = og / nx;
;             if (og + 1u == (tg + 1u) * nx) xb_add(&bar[XB_TOPGEN], 1u);
;             else XB_SPIN(xb_ld(&bar[XB_TOPGEN]) == tg, bar);
;             __builtin_amdgcn_fence(__ATOMIC_ACQUIRE, "agent");
;             xb_add(&bar[XB_XGEN(b.x)], 1u);
;             asm volatile("s_waitcnt vmcnt(0)" ::: "memory");
;         } else {
;             XB_SPIN(xb_ld(&bar[XB_XGEN(b.x)]) == gen, bar);
;             __builtin_amdgcn_fence(__ATOMIC_ACQUIRE, "agent");
;             asm volatile("s_waitcnt vmcnt(0)" ::: "memory");
;         }
.LBB0_711:
	s_or_b64 exec, exec, s[8:9]
	v_cvt_f32_u32_e32 v4, v2
	s_waitcnt vmcnt(0)
	v_readfirstlane_b32 s4, v3
	v_sub_u32_e32 v3, 0, v2
	v_rcp_iflag_f32_e32 v4, v4
	v_add_u32_e32 v5, s4, v1
	v_mul_f32_e32 v4, 0x4f7ffffe, v4
	v_cvt_u32_f32_e32 v4, v4
	v_mul_lo_u32 v1, v3, v4
	v_mul_hi_u32 v1, v4, v1
	v_add_u32_e32 v1, v4, v1
	v_mul_hi_u32 v1, v5, v1
	v_mul_lo_u32 v3, v1, v2
	v_sub_u32_e32 v3, v5, v3
	v_add_u32_e32 v4, 1, v1
	v_cmp_ge_u32_e32 vcc, v3, v2
	s_nop 1
	v_cndmask_b32_e32 v1, v1, v4, vcc
	v_sub_u32_e32 v4, v3, v2
	v_cndmask_b32_e32 v3, v3, v4, vcc
	v_add_u32_e32 v4, 1, v1
	v_cmp_ge_u32_e32 vcc, v3, v2
	v_add_u32_e32 v3, 1, v5
	s_nop 0
	v_cndmask_b32_e32 v1, v1, v4, vcc
	v_mul_lo_u32 v4, v2, v1
	v_add_u32_e32 v2, v4, v2
	v_cmp_ne_u32_e32 vcc, v3, v2
	s_and_saveexec_b64 s[4:5], vcc
	s_xor_b64 s[4:5], exec, s[4:5]
	s_cbranch_execz .LBB0_730
	s_waitcnt lgkmcnt(0)
	v_mov_b32_e32 v0, 0x3500
	global_load_dword v0, v0, s[34:35] sc1
	s_add_u32 s24, s34, 0x3500
	s_addc_u32 s25, s35, 0
	s_waitcnt vmcnt(0)
	v_cmp_eq_u32_e32 vcc, v0, v1
	s_and_saveexec_b64 s[8:9], vcc
	s_cbranch_execz .LBB0_729
	s_add_u32 s22, s30, 0x20200
	s_addc_u32 s23, s31, 0
	s_mov_b32 s46, 1
	s_mov_b64 s[36:37], 0
	v_mov_b32_e32 v0, 0
	s_branch .LBB0_715

; __device__ __forceinline__ unsigned xb_ld(unsigned* p)              { return __hip_atomic_load(p, __ATOMIC_RELAXED, __HIP_MEMORY_SCOPE_AGENT); }
; __device__ __forceinline__ unsigned xb_add(unsigned* p, unsigned v) { return __hip_atomic_fetch_add(p, v, __ATOMIC_RELAXED, __HIP_MEMORY_SCOPE_AGENT); }
; #define XB_SPIN(cond, bar) do { unsigned _sp = 0; while (cond) { __builtin_amdgcn_s_sleep(1); \
;     if ((++_sp & 255u) == 0u) { if (xb_ld(&(bar)[XB_TMO])) break; if (_sp > XB_SPIN_CAP) { atomicAdd(&(bar)[XB_TMO], 1u); break; } } } } while (0)
; __device__ __forceinline__ void xcd_barrier(const XcdBarrier& b) {
;     ...
;         const unsigned old = xb_add(&bar[XB_XSUB(b.x)], 1u);
;         const unsigned gen = old / nloc;
;         if (old + 1u == (gen + 1u) * nloc) {
;             __builtin_amdgcn_fence(__ATOMIC_RELEASE, "agent");
;             asm volatile("s_waitcnt vmcnt(0)" ::: "memory");
;             const unsigned og = xb_add(&bar[XB_TOP], 1u);
;             const unsigned tg = og / nx;
;             if (og + 1u == (tg + 1u) * nx) xb_add(&bar[XB_TOPGEN], 1u);
;             else XB_SPIN(xb_ld(&bar[XB_TOPGEN]) == tg, bar);
;             __builtin_amdgcn_fence(__ATOMIC_ACQUIRE, "agent");
;             xb_add(&bar[XB_XGEN(b.x)], 1u);
;             asm volatile("s_waitcnt vmcnt(0)" ::: "memory");
;         } else {
;             XB_SPIN(xb_ld(&bar[XB_XGEN(b.x)]) == gen, bar);
;             __builtin_amdgcn_fence(__ATOMIC_ACQUIRE, "agent");
;             asm volatile("s_waitcnt vmcnt(0)" ::: "memory");
;         }
.LBB0_781:
	s_or_b64 exec, exec, s[20:21]
	v_cvt_f32_u32_e32 v4, v2
	s_waitcnt vmcnt(0)
	v_readfirstlane_b32 s8, v3
	v_sub_u32_e32 v3, 0, v2
	v_rcp_iflag_f32_e32 v4, v4
	v_add_u32_e32 v5, s8, v1
	v_mul_f32_e32 v4, 0x4f7ffffe, v4
	v_cvt_u32_f32_e32 v4, v4
	v_mul_lo_u32 v1, v3, v4
	v_mul_hi_u32 v1, v4, v1
	v_add_u32_e32 v1, v4, v1
	v_mul_hi_u32 v1, v5, v1
	v_mul_lo_u32 v3, v1, v2
	v_sub_u32_e32 v3, v5, v3
	v_add_u32_e32 v4, 1, v1
	v_cmp_ge_u32_e32 vcc, v3, v2
	s_nop 1
	v_cndmask_b32_e32 v1, v1, v4, vcc
	v_sub_u32_e32 v4, v3, v2
	v_cndmask_b32_e32 v3, v3, v4, vcc
	v_add_u32_e32 v4, 1, v1
	v_cmp_ge_u32_e32 vcc, v3, v2
	v_add_u32_e32 v3, 1, v5
	s_nop 0
	v_cndmask_b32_e32 v1, v1, v4, vcc
	v_mul_lo_u32 v4, v2, v1
	v_add_u32_e32 v2, v4, v2
	v_cmp_ne_u32_e32 vcc, v3, v2
	s_and_saveexec_b64 s[8:9], vcc
	s_xor_b64 s[8:9], exec, s[8:9]
	s_cbranch_execz .LBB0_795
	s_waitcnt lgkmcnt(0)
	v_mov_b32_e32 v0, 0x3500
	global_load_dword v0, v0, s[34:35] sc1
	s_add_u32 s24, s34, 0x3500
	s_addc_u32 s25, s35, 0
	s_waitcnt vmcnt(0)
	v_cmp_eq_u32_e32 vcc, v0, v1
	s_and_saveexec_b64 s[20:21], vcc
	s_cbranch_execz .LBB0_794
	s_add_u32 s22, s30, 0x20200
	s_addc_u32 s23, s31, 0
	s_mov_b32 s46, 1
	s_mov_b64 s[36:37], 0
	v_mov_b32_e32 v0, 0
	s_branch .LBB0_785

; __device__ __forceinline__ unsigned xb_ld(unsigned* p)              { return __hip_atomic_load(p, __ATOMIC_RELAXED, __HIP_MEMORY_SCOPE_AGENT); }
; __device__ __forceinline__ unsigned xb_add(unsigned* p, unsigned v) { return __hip_atomic_fetch_add(p, v, __ATOMIC_RELAXED, __HIP_MEMORY_SCOPE_AGENT); }
; #define XB_SPIN(cond, bar) do { unsigned _sp = 0; while (cond) { __builtin_amdgcn_s_sleep(1); \
;     if ((++_sp & 255u) == 0u) { if (xb_ld(&(bar)[XB_TMO])) break; if (_sp > XB_SPIN_CAP) { atomicAdd(&(bar)[XB_TMO], 1u); break; } } } } while (0)
; __device__ __forceinline__ void xcd_barrier(const XcdBarrier& b) {
;     ...
;         const unsigned old = xb_add(&bar[XB_XSUB(b.x)], 1u);
;         const unsigned gen = old / nloc;
;         if (old + 1u == (gen + 1u) * nloc) {
;             __builtin_amdgcn_fence(__ATOMIC_RELEASE, "agent");
;             asm volatile("s_waitcnt vmcnt(0)" ::: "memory");
;             const unsigned og = xb_add(&bar[XB_TOP], 1u);
;             const unsigned tg = og / nx;
;             if (og + 1u == (tg + 1u) * nx) xb_add(&bar[XB_TOPGEN], 1u);
;             else XB_SPIN(xb_ld(&bar[XB_TOPGEN]) == tg, bar);
;             __builtin_amdgcn_fence(__ATOMIC_ACQUIRE, "agent");
;             xb_add(&bar[XB_XGEN(b.x)], 1u);
;             asm volatile("s_waitcnt vmcnt(0)" ::: "memory");
;         } else {
;             XB_SPIN(xb_ld(&bar[XB_XGEN(b.x)]) == gen, bar);
;             __builtin_amdgcn_fence(__ATOMIC_ACQUIRE, "agent");
;             asm volatile("s_waitcnt vmcnt(0)" ::: "memory");
;         }
.LBB0_860:
	s_or_b64 exec, exec, s[8:9]
	v_cvt_f32_u32_e32 v4, v2
	s_waitcnt vmcnt(0)
	v_readfirstlane_b32 s6, v3
	v_sub_u32_e32 v3, 0, v2
	v_rcp_iflag_f32_e32 v4, v4
	v_add_u32_e32 v5, s6, v1
	v_mul_f32_e32 v4, 0x4f7ffffe, v4
	v_cvt_u32_f32_e32 v4, v4
	v_mul_lo_u32 v1, v3, v4
	v_mul_hi_u32 v1, v4, v1
	v_add_u32_e32 v1, v4, v1
	v_mul_hi_u32 v1, v5, v1
	v_mul_lo_u32 v3, v1, v2
	v_sub_u32_e32 v3, v5, v3
	v_add_u32_e32 v4, 1, v1
	v_cmp_ge_u32_e32 vcc, v3, v2
	s_nop 1
	v_cndmask_b32_e32 v1, v1, v4, vcc
	v_sub_u32_e32 v4, v3, v2
	v_cndmask_b32_e32 v3, v3, v4, vcc
	v_add_u32_e32 v4, 1, v1
	v_cmp_ge_u32_e32 vcc, v3, v2
	v_add_u32_e32 v3, 1, v5
	s_nop 0
	v_cndmask_b32_e32 v1, v1, v4, vcc
	v_mul_lo_u32 v4, v2, v1
	v_add_u32_e32 v2, v4, v2
	v_cmp_ne_u32_e32 vcc, v3, v2
	s_and_saveexec_b64 s[6:7], vcc
	s_xor_b64 s[6:7], exec, s[6:7]
	s_cbranch_execz .LBB0_874
	s_waitcnt lgkmcnt(0)
	v_mov_b32_e32 v0, 0x3500
	global_load_dword v0, v0, s[34:35] sc1
	s_add_u32 s20, s34, 0x3500
	s_addc_u32 s21, s35, 0
	s_waitcnt vmcnt(0)
	v_cmp_eq_u32_e32 vcc, v0, v1
	s_and_saveexec_b64 s[8:9], vcc
	s_cbranch_execz .LBB0_873
	s_add_u32 s18, s30, 0x20200
	s_addc_u32 s19, s31, 0
	s_mov_b32 s13, 1
	s_mov_b64 s[22:23], 0
	v_mov_b32_e32 v0, 0
	s_branch .LBB0_864
